# variant: P0 deferral on a quarter of CUs (XCDs 3 and 7)
# baseline (speedup 1.0000x reference)
.LBB0_128:
	s_or_b64 exec, exec, s[0:1]
	s_and_b32 s98, s2, 3
	s_cmp_eq_u32 s98, 3
	s_cbranch_scc0 .Lp1_skipdefer
	v_writelane_b32 v234, s0, 0
	v_writelane_b32 v234, s1, 1
	v_writelane_b32 v234, s2, 2
	v_writelane_b32 v234, s3, 3
	v_writelane_b32 v234, s4, 4
	v_writelane_b32 v234, s5, 5
	v_writelane_b32 v234, s6, 6
	v_writelane_b32 v234, s7, 7
	v_writelane_b32 v234, s8, 8
	v_writelane_b32 v234, s9, 9
	v_writelane_b32 v234, s10, 10
	v_writelane_b32 v234, s11, 11
	v_writelane_b32 v234, s12, 12
	v_writelane_b32 v234, s13, 13
	v_writelane_b32 v234, s14, 14
	v_writelane_b32 v234, s15, 15
	v_writelane_b32 v234, s16, 16
	v_writelane_b32 v234, s17, 17
	v_writelane_b32 v234, s18, 18
	v_writelane_b32 v234, s19, 19
	v_writelane_b32 v234, s20, 20
	v_writelane_b32 v234, s21, 21
	v_writelane_b32 v234, s22, 22
	v_writelane_b32 v234, s23, 23
	v_writelane_b32 v234, s24, 24
	v_writelane_b32 v234, s25, 25
	v_writelane_b32 v234, s26, 26
	v_writelane_b32 v234, s27, 27
	v_writelane_b32 v234, s28, 28
	v_writelane_b32 v234, s29, 29
	v_writelane_b32 v234, s30, 30
	v_writelane_b32 v234, s31, 31
	v_writelane_b32 v234, s32, 32
	v_writelane_b32 v234, s33, 33
	v_writelane_b32 v234, s34, 34
	v_writelane_b32 v234, s35, 35
	v_writelane_b32 v234, s36, 36
	v_writelane_b32 v234, s37, 37
	v_writelane_b32 v234, s38, 38
	v_writelane_b32 v234, s39, 39
	v_writelane_b32 v234, s40, 40
	v_writelane_b32 v234, s41, 41
	v_writelane_b32 v234, s42, 42
	v_writelane_b32 v234, s43, 43
	v_writelane_b32 v234, s44, 44
	v_writelane_b32 v234, s45, 45
	v_writelane_b32 v234, s46, 46
	v_writelane_b32 v234, s47, 47
	v_writelane_b32 v234, s48, 48
	v_writelane_b32 v234, s49, 49
	v_writelane_b32 v234, s50, 50
	v_writelane_b32 v234, s51, 51
	v_writelane_b32 v234, s52, 52
	v_writelane_b32 v234, s53, 53
	v_writelane_b32 v234, s54, 54
	v_writelane_b32 v234, s55, 55
	v_writelane_b32 v234, s56, 56
	v_writelane_b32 v234, s57, 57
	v_writelane_b32 v234, s58, 58
	v_writelane_b32 v234, s59, 59
	v_writelane_b32 v234, s60, 60
	v_writelane_b32 v234, s61, 61
	v_writelane_b32 v234, s62, 62
	v_writelane_b32 v234, s63, 63
	v_writelane_b32 v235, s64, 0
	v_writelane_b32 v235, s65, 1
	v_writelane_b32 v235, s66, 2
	v_writelane_b32 v235, s67, 3
	v_writelane_b32 v235, s68, 4
	v_writelane_b32 v235, s69, 5
	v_writelane_b32 v235, s70, 6
	v_writelane_b32 v235, s71, 7
	v_writelane_b32 v235, s72, 8
	v_writelane_b32 v235, s73, 9
	v_writelane_b32 v235, s74, 10
	v_writelane_b32 v235, s75, 11
	v_writelane_b32 v235, s76, 12
	v_writelane_b32 v235, s77, 13
	v_writelane_b32 v235, s78, 14
	v_writelane_b32 v235, s79, 15
	v_writelane_b32 v235, s80, 16
	v_writelane_b32 v235, s81, 17
	v_writelane_b32 v235, s82, 18
	v_writelane_b32 v235, s83, 19
	v_writelane_b32 v235, s84, 20
	v_writelane_b32 v235, s85, 21
	v_writelane_b32 v235, s86, 22
	v_writelane_b32 v235, s87, 23
	v_writelane_b32 v235, s88, 24
	v_writelane_b32 v235, s89, 25
	v_writelane_b32 v235, s90, 26
	v_writelane_b32 v235, s91, 27
	v_writelane_b32 v235, s92, 28
	v_writelane_b32 v235, s93, 29
	v_writelane_b32 v235, s94, 30
	v_writelane_b32 v235, s95, 31
	v_writelane_b32 v235, s96, 32
	v_writelane_b32 v235, s97, 33
	v_writelane_b32 v235, vcc_lo, 34
	v_writelane_b32 v235, vcc_hi, 35
	v_readlane_b32 s72, v233, 47
	v_readlane_b32 s73, v233, 48
	v_readlane_b32 s74, v233, 49
	v_readlane_b32 s75, v233, 50
	v_readlane_b32 s76, v233, 51
	v_readlane_b32 s77, v233, 52
	s_add_u32 s62, s92, 0x400000
	s_addc_u32 s63, s93, 0
	v_mov_b32_e32 v1, v210
	s_nop 0
	v_readfirstlane_b32 s0, v1
	v_and_b32_e32 v76, 63, v1
	s_nop 3
	s_ashr_i32 s8, s0, 6
	s_lshr_b32 s1, s2, 2
	s_lshl_b32 s1, s1, 0
	s_and_b32 s3, s2, 0
	s_or_b32 s1, s1, s3
	s_lshl_b32 s1, s1, 3
	s_add_i32 s26, s8, s1
	s_addk_i32 s26, 0x1000
	s_movk_i32 s96, 0x200
	s_movk_i32 s101, 0x247f
	s_mov_b32 s100, 1
	s_branch .Lp0_setup
